# loop-edge (7.12): attention A step tails - constant-false rescale test replaced by a direct branch, redundant v_max x,x canonicalisations and the 0+x start of the row-sum chain removed
# speedup vs baseline: 1.0050x; 1.0008x over previous
; #define ATT_PKN(P, BASE, OUT) do { u32x4 w = {cvtpk(P[BASE + 0], P[BASE + 1]), cvtpk(P[BASE + 2], P[BASE + 3]), cvtpk(P[BASE + 4], P[BASE + 5]), cvtpk(P[BASE + 6], P[BASE + 7])}; OUT = *reinterpret_cast<bf16x8*>(&w); } while (0)
; __device__ __forceinline__ void finishSM(f32x16& p0, f32x16& p1, float alpha, float& l_reg, bf16x8& pa0, bf16x8& pa1, bf16x8& pa2, bf16x8& pa3) {
; #pragma unroll
;   for (int r = 0; r < 16; ++r) p1[r] = __builtin_amdgcn_exp2f(p1[r]);
;   float ps = 0;
; #pragma unroll
;   for (int r = 0; r < 16; ++r) ps += p0[r];
; #pragma unroll
;   for (int r = 0; r < 16; ++r) ps += p1[r];
;   { auto rr = __builtin_amdgcn_permlane32_swap(__float_as_uint(ps), __float_as_uint(ps), false, false);
;     ps = __uint_as_float(rr[0]) + __uint_as_float(rr[1]); }
;   l_reg = l_reg * alpha + ps;
;     ...
;   ATT_PKN(p0, 0, pa0); ATT_PKN(p0, 8, pa1); ATT_PKN(p1, 0, pa2); ATT_PKN(p1, 8, pa3);
;     ...
; }
; __device__ __forceinline__ void qkt(f32x16& p0, f32x16& p1, const bf16* Ks, const bf16x8* qr, int r32, int hi, int mp, const f32x16& negm) {
; #pragma unroll
;   for (int d0 = 0; d0 < 4; ++d0) { int cb = ((mp * 4 + d0) * 16 + hi * 8) * 2;
;     bf16x8 b0 = *reinterpret_cast<const bf16x8*>((const char*)Ks + KSWZ(r32, cb));
;     bf16x8 b1 = *reinterpret_cast<const bf16x8*>((const char*)Ks + KSWZ(32 + r32, cb));
;     if (d0 == 0) { p0 = __builtin_amdgcn_mfma_f32_32x32x16_bf16(b0, qr[0], negm, 0, 0, 0); p1 = __builtin_amdgcn_mfma_f32_32x32x16_bf16(b1, qr[0], negm, 0, 0, 0); }
;     else { p0 = __builtin_amdgcn_mfma_f32_32x32x16_bf16(b0, qr[d0], p0, 0, 0, 0); p1 = __builtin_amdgcn_mfma_f32_32x32x16_bf16(b1, qr[d0], p1, 0, 0, 0); } }
; }
.Lprio_skip:
.LBB0_197:
	s_add_i32 s10, s39, 0
	v_add_u32_e32 v112, s10, v202
	ds_read_b128 v[236:239], v112 offset:24576
	ds_read_b128 v[112:115], v112 offset:16384
	v_add_u32_e32 v208, s10, v201
	ds_read_b128 v[68:71], v208 offset:24576
	ds_read_b128 v[72:75], v208 offset:16384
	v_add_u32_e32 v208, s10, v199
	v_exp_f32_e32 v210, v96
	v_add_f32_e32 v96, v174, v172
	s_waitcnt lgkmcnt(2)
	v_mfma_f32_32x32x16_bf16 v[128:143], v[112:115], v[158:161], v[80:95]
	v_add_f32_e32 v96, v175, v96
	v_add_f32_e32 v96, v211, v96
	v_mfma_f32_32x32x16_bf16 v[112:127], v[236:239], v[158:161], v[80:95]
	ds_read_b128 v[236:239], v208 offset:24576
	ds_read_b128 v[240:243], v208 offset:16384
	v_add_u32_e32 v208, s10, v183
	v_add_f32_e32 v96, v212, v96
	v_add_f32_e32 v96, v215, v96
	v_add_f32_e32 v96, v216, v96
	v_add_f32_e32 v96, v233, v96
	v_add_f32_e32 v96, v173, v96
	s_waitcnt lgkmcnt(2)
	v_mfma_f32_32x32x16_bf16 v[112:127], v[68:71], v[154:157], v[112:127]
	v_add_f32_e32 v96, v176, v96
	v_add_f32_e32 v96, v177, v96
	v_add_f32_e32 v96, v213, v96
	v_add_f32_e32 v96, v214, v96
	v_exp_f32_e32 v235, v97
	v_add_f32_e32 v96, v217, v96
	v_add_f32_e32 v96, v232, v96
	v_mfma_f32_32x32x16_bf16 v[128:143], v[72:75], v[154:157], v[128:143]
	ds_read_b128 v[68:71], v208 offset:24576
	ds_read_b128 v[72:75], v208 offset:16384
	v_add_f32_e32 v96, v234, v96
	v_add_f32_e32 v96, v210, v96
	v_add_f32_e32 v96, v235, v96
	v_exp_f32_e32 v244, v106
	v_exp_f32_e32 v245, v107
	s_waitcnt lgkmcnt(2)
	v_mfma_f32_32x32x16_bf16 v[112:127], v[236:239], v[150:153], v[112:127]
	v_exp_f32_e32 v246, v108
	v_exp_f32_e32 v247, v109
	v_exp_f32_e32 v248, v110
	v_exp_f32_e32 v111, v111
	v_cvt_pk_bf16_f32 v97, v175, v211
	v_cvt_pk_bf16_f32 v109, v244, v245
	v_cvt_pk_bf16_f32 v110, v246, v247
	v_mfma_f32_32x32x16_bf16 v[128:143], v[240:243], v[150:153], v[128:143]
	s_waitcnt lgkmcnt(0)
	v_mfma_f32_32x32x16_bf16 v[112:127], v[68:71], v[146:149], v[112:127]
	v_exp_f32_e32 v236, v98
	v_exp_f32_e32 v237, v99
	v_exp_f32_e32 v238, v100
	v_exp_f32_e32 v239, v101
	v_add_f32_e32 v96, v236, v96
	v_add_f32_e32 v96, v237, v96
	v_add_f32_e32 v96, v238, v96
	v_mfma_f32_32x32x16_bf16 v[128:143], v[72:75], v[146:149], v[128:143]
	v_exp_f32_e32 v240, v102
	v_exp_f32_e32 v241, v103
	v_exp_f32_e32 v242, v104
	v_exp_f32_e32 v243, v105
	v_add_f32_e32 v96, v239, v96
	v_add_f32_e32 v96, v240, v96
	v_add_f32_e32 v96, v241, v96
	v_add_f32_e32 v96, v242, v96
	v_add_f32_e32 v96, v243, v96
	v_add_f32_e32 v96, v244, v96
	v_add_f32_e32 v96, v245, v96
	v_add_f32_e32 v96, v246, v96
	v_add_f32_e32 v96, v247, v96
	v_add_f32_e32 v96, v248, v96
	v_add_f32_e32 v208, v111, v96
	v_mov_b32_e32 v209, v208
	s_nop 1
	v_permlane32_swap_b32_e32 v208, v209
	v_cvt_pk_bf16_f32 v96, v172, v174
	v_cvt_pk_bf16_f32 v98, v212, v215
	v_cvt_pk_bf16_f32 v99, v216, v233
	v_cvt_pk_bf16_f32 v100, v173, v176
	v_cvt_pk_bf16_f32 v101, v177, v213
	v_cvt_pk_bf16_f32 v102, v214, v217
	v_cvt_pk_bf16_f32 v103, v232, v234
	v_cvt_pk_bf16_f32 v104, v210, v235
	v_cvt_pk_bf16_f32 v105, v236, v237
	v_cvt_pk_bf16_f32 v106, v238, v239
	v_cvt_pk_bf16_f32 v107, v240, v241
	v_cvt_pk_bf16_f32 v108, v242, v243
	v_cvt_pk_bf16_f32 v111, v248, v111
	v_add_u32_e32 v240, s48, v205
	ds_read_b64_tr_b16 v[210:211], v240 offset:0
	ds_read_b64_tr_b16 v[212:213], v240 offset:0x800
	ds_read_b64_tr_b16 v[214:215], v240 offset:0x1000
	ds_read_b64_tr_b16 v[216:217], v240 offset:0x1800
	ds_read_b64_tr_b16 v[232:233], v240 offset:0x2000
	ds_read_b64_tr_b16 v[234:235], v240 offset:0x2800
	ds_read_b64_tr_b16 v[236:237], v240 offset:0x3000
	ds_read_b64_tr_b16 v[238:239], v240 offset:0x3800
	s_add_i32 s12, s21, s56
	s_add_u32 s98, s50, s36
	s_addc_u32 s99, s51, s37
	s_add_u32 s100, s50, 0x4030000
	s_addc_u32 s101, s51, 0
	s_add_i32 m0, s12, 0x4000
	s_add_u32 s10, s100, 0x80
	s_addc_u32 s11, s101, 0
	global_load_lds_dwordx4 v168, s[98:99]
	s_mov_b32 m0, s12
	s_nop 0
	global_load_lds_dwordx4 v188, s[100:101]
	s_add_i32 m0, s12, 0x4400
	s_nop 0
	global_load_lds_dwordx4 v170, s[98:99]
	s_add_i32 m0, s12, 0x400
	s_nop 0
	global_load_lds_dwordx4 v188, s[10:11]
	s_waitcnt lgkmcnt(0)
; #define SBAR() __builtin_amdgcn_sched_barrier(0)
; template <int OFF> __device__ __forceinline__ s16x4 tr_read(int vb) { s16x4 r; asm volatile("ds_read_b64_tr_b16 %0, %1 offset:%2" : "=&v"(r) : "v"(vb), "i"(OFF) : "memory"); return r; }
; template <bool FIRST> __device__ __forceinline__ void partialSM(f32x16& p0, f32x16& p1, float& m_reg, f32x16& negm, float& alpha) {
;   float pmax = p0[0];
; #pragma unroll
;   for (int r = 1; r < 16; ++r) pmax = fmaxf(pmax, p0[r]);
; #pragma unroll
;   for (int r = 0; r < 16; ++r) pmax = fmaxf(pmax, p1[r]);
;   { auto rr = __builtin_amdgcn_permlane32_swap(__float_as_uint(pmax), __float_as_uint(pmax), false, false);
;     pmax = fmaxf(__uint_as_float(rr[0]), __uint_as_float(rr[1])); }
;   alpha = 1.f;
;   if (FIRST || __builtin_expect(__any(pmax > THR), 0)) { const float dl = FIRST ? pmax : fmaxf(pmax, 0.f); m_reg += dl; if (!FIRST) alpha = __builtin_amdgcn_exp2f(-dl);
; template <int D0> __device__ __forceinline__ void pv_one(f32x16& od, int vb, bf16x8 pa0, bf16x8 pa1, bf16x8 pa2, bf16x8 pa3) {
;   const s16x4 l0 = tr_read<v_rd_off(D0, 0, 0)>(vb), h0 = tr_read<v_rd_off(D0, 0, 1)>(vb), l1 = tr_read<v_rd_off(D0, 1, 0)>(vb), h1 = tr_read<v_rd_off(D0, 1, 1)>(vb);
;   const s16x4 l2 = tr_read<v_rd_off(D0, 2, 0)>(vb), h2 = tr_read<v_rd_off(D0, 2, 1)>(vb), l3 = tr_read<v_rd_off(D0, 3, 0)>(vb), h3 = tr_read<v_rd_off(D0, 3, 1)>(vb);
;   asm volatile("s_waitcnt lgkmcnt(0)" ::: "memory"); SBAR();
;   od = __builtin_amdgcn_mfma_f32_32x32x16_bf16(pa0, ATT_PK(l0, h0), od, 0, 0, 0);
;   od = __builtin_amdgcn_mfma_f32_32x32x16_bf16(pa1, ATT_PK(l1, h1), od, 0, 0, 0);
;   od = __builtin_amdgcn_mfma_f32_32x32x16_bf16(pa2, ATT_PK(l2, h2), od, 0, 0, 0);
;   od = __builtin_amdgcn_mfma_f32_32x32x16_bf16(pa3, ATT_PK(l3, h3), od, 0, 0, 0);
; }
; __device__ __forceinline__ void pv_d0(f32x16* o, int vb, bf16x8 pa0, bf16x8 pa1, bf16x8 pa2, bf16x8 pa3) {
;   pv_one<0>(o[0], vb, pa0, pa1, pa2, pa3); pv_one<1>(o[1], vb, pa0, pa1, pa2, pa3); pv_one<2>(o[2], vb, pa0, pa1, pa2, pa3); pv_one<3>(o[3], vb, pa0, pa1, pa2, pa3);
	s_nop 0
	v_mfma_f32_32x32x16_bf16 v[0:15], v[96:99], v[210:213], v[0:15]
	ds_read_b64_tr_b16 v[210:211], v240 offset:0x200
	ds_read_b64_tr_b16 v[212:213], v240 offset:0xa00
	v_mfma_f32_32x32x16_bf16 v[0:15], v[100:103], v[214:217], v[0:15]
	ds_read_b64_tr_b16 v[214:215], v240 offset:0x1200
	ds_read_b64_tr_b16 v[216:217], v240 offset:0x1a00
	v_mfma_f32_32x32x16_bf16 v[0:15], v[104:107], v[232:235], v[0:15]
	ds_read_b64_tr_b16 v[232:233], v240 offset:0x2200
	ds_read_b64_tr_b16 v[234:235], v240 offset:0x2a00
	v_mfma_f32_32x32x16_bf16 v[0:15], v[108:111], v[236:239], v[0:15]
	ds_read_b64_tr_b16 v[236:237], v240 offset:0x3200
	ds_read_b64_tr_b16 v[238:239], v240 offset:0x3a00
	s_waitcnt lgkmcnt(0)
	v_mfma_f32_32x32x16_bf16 v[48:63], v[96:99], v[210:213], v[48:63]
	ds_read_b64_tr_b16 v[210:211], v240 offset:0x400
	ds_read_b64_tr_b16 v[212:213], v240 offset:0xc00
	v_mfma_f32_32x32x16_bf16 v[48:63], v[100:103], v[214:217], v[48:63]
	ds_read_b64_tr_b16 v[214:215], v240 offset:0x1400
	ds_read_b64_tr_b16 v[216:217], v240 offset:0x1c00
	v_mfma_f32_32x32x16_bf16 v[48:63], v[104:107], v[232:235], v[48:63]
	ds_read_b64_tr_b16 v[232:233], v240 offset:0x2400
	ds_read_b64_tr_b16 v[234:235], v240 offset:0x2c00
	v_mfma_f32_32x32x16_bf16 v[48:63], v[108:111], v[236:239], v[48:63]
	ds_read_b64_tr_b16 v[236:237], v240 offset:0x3400
	ds_read_b64_tr_b16 v[238:239], v240 offset:0x3c00
	s_waitcnt lgkmcnt(0)
	v_mfma_f32_32x32x16_bf16 v[32:47], v[96:99], v[210:213], v[32:47]
	ds_read_b64_tr_b16 v[210:211], v240 offset:0x600
	ds_read_b64_tr_b16 v[212:213], v240 offset:0xe00
	v_mfma_f32_32x32x16_bf16 v[32:47], v[100:103], v[214:217], v[32:47]
	ds_read_b64_tr_b16 v[214:215], v240 offset:0x1600
	ds_read_b64_tr_b16 v[216:217], v240 offset:0x1e00
	v_mfma_f32_32x32x16_bf16 v[32:47], v[104:107], v[232:235], v[32:47]
	ds_read_b64_tr_b16 v[232:233], v240 offset:0x2600
	ds_read_b64_tr_b16 v[234:235], v240 offset:0x2e00
	v_mfma_f32_32x32x16_bf16 v[32:47], v[108:111], v[236:239], v[32:47]
	ds_read_b64_tr_b16 v[236:237], v240 offset:0x3600
	ds_read_b64_tr_b16 v[238:239], v240 offset:0x3e00
	s_waitcnt lgkmcnt(0)
	v_mfma_f32_32x32x16_bf16 v[16:31], v[96:99], v[210:213], v[16:31]
	v_max_f32_e32 v96, v129, v129
	v_max_f32_e32 v97, v128, v128
	v_max_f32_e32 v96, v97, v96
	v_max3_f32 v96, v96, v130, v131
	v_max3_f32 v96, v96, v132, v133
	v_max3_f32 v96, v96, v134, v135
	v_max3_f32 v96, v96, v136, v137
	v_mfma_f32_32x32x16_bf16 v[16:31], v[100:103], v[214:217], v[16:31]
	v_max3_f32 v96, v96, v138, v139
	v_max3_f32 v96, v96, v140, v141
	v_max3_f32 v96, v96, v142, v143
	v_max3_f32 v96, v96, v112, v113
	v_max3_f32 v96, v96, v114, v115
	v_max3_f32 v96, v96, v116, v117
	v_max3_f32 v96, v96, v118, v119
	v_mfma_f32_32x32x16_bf16 v[16:31], v[104:107], v[232:235], v[16:31]
	v_max3_f32 v96, v96, v120, v121
	v_max3_f32 v96, v96, v122, v123
	v_max3_f32 v96, v96, v124, v125
	v_max3_f32 v96, v96, v126, v127
	v_mov_b32_e32 v97, v96
	s_nop 1
	v_permlane32_swap_b32_e32 v96, v97
	v_mfma_f32_32x32x16_bf16 v[16:31], v[108:111], v[236:239], v[16:31]
	v_max_f32_e32 v96, v96, v97
	v_cmp_lt_f32_e32 vcc, s19, v96
	s_cbranch_vccnz .LBB0_215
	v_mov_b32_e32 v210, 1.0
	s_branch .LBB0_202

; #define SBAR() __builtin_amdgcn_sched_barrier(0)
; template <int OFF> __device__ __forceinline__ s16x4 tr_read(int vb) { s16x4 r; asm volatile("ds_read_b64_tr_b16 %0, %1 offset:%2" : "=&v"(r) : "v"(vb), "i"(OFF) : "memory"); return r; }
; __device__ __forceinline__ void finishSM(f32x16& p0, f32x16& p1, float alpha, float& l_reg, bf16x8& pa0, bf16x8& pa1, bf16x8& pa2, bf16x8& pa3) {
; #pragma unroll
;   for (int r = 0; r < 16; ++r) p1[r] = __builtin_amdgcn_exp2f(p1[r]);
;   float ps = 0;
; #pragma unroll
;   for (int r = 0; r < 16; ++r) ps += p0[r];
; #pragma unroll
;   for (int r = 0; r < 16; ++r) ps += p1[r];
;   { auto rr = __builtin_amdgcn_permlane32_swap(__float_as_uint(ps), __float_as_uint(ps), false, false);
;     ps = __uint_as_float(rr[0]) + __uint_as_float(rr[1]); }
;   l_reg = l_reg * alpha + ps;
;     ...
;   ATT_PKN(p0, 0, pa0); ATT_PKN(p0, 8, pa1); ATT_PKN(p1, 0, pa2); ATT_PKN(p1, 8, pa3);
;     ...
; }
; __device__ __forceinline__ void qkt(f32x16& p0, f32x16& p1, const bf16* Ks, const bf16x8* qr, int r32, int hi, int mp, const f32x16& negm) {
; #pragma unroll
;   for (int d0 = 0; d0 < 4; ++d0) { int cb = ((mp * 4 + d0) * 16 + hi * 8) * 2;
;     bf16x8 b0 = *reinterpret_cast<const bf16x8*>((const char*)Ks + KSWZ(r32, cb));
;     bf16x8 b1 = *reinterpret_cast<const bf16x8*>((const char*)Ks + KSWZ(32 + r32, cb));
;     if (d0 == 0) { p0 = __builtin_amdgcn_mfma_f32_32x32x16_bf16(b0, qr[0], negm, 0, 0, 0); p1 = __builtin_amdgcn_mfma_f32_32x32x16_bf16(b1, qr[0], negm, 0, 0, 0); }
;     else { p0 = __builtin_amdgcn_mfma_f32_32x32x16_bf16(b0, qr[d0], p0, 0, 0, 0); p1 = __builtin_amdgcn_mfma_f32_32x32x16_bf16(b1, qr[d0], p1, 0, 0, 0); } }
; }
; __device__ __forceinline__ int v_st(int k, int c) { const int kk = k; return ((kk >> 3) * 4 + (c >> 5)) * 512 + ((kk & 7) * 32 + (c & 31)) * 2; }
; template <int D0> __device__ __forceinline__ void pv_one(f32x16& od, int vb, bf16x8 pa0, bf16x8 pa1, bf16x8 pa2, bf16x8 pa3) {
;   const s16x4 l0 = tr_read<v_rd_off(D0, 0, 0)>(vb), h0 = tr_read<v_rd_off(D0, 0, 1)>(vb), l1 = tr_read<v_rd_off(D0, 1, 0)>(vb), h1 = tr_read<v_rd_off(D0, 1, 1)>(vb);
;   const s16x4 l2 = tr_read<v_rd_off(D0, 2, 0)>(vb), h2 = tr_read<v_rd_off(D0, 2, 1)>(vb), l3 = tr_read<v_rd_off(D0, 3, 0)>(vb), h3 = tr_read<v_rd_off(D0, 3, 1)>(vb);
;   asm volatile("s_waitcnt lgkmcnt(0)" ::: "memory"); SBAR();
.LBB0_202:
	v_exp_f32_e32 v211, v128
	v_exp_f32_e32 v213, v129
	v_exp_f32_e32 v214, v130
	v_exp_f32_e32 v217, v131
	v_exp_f32_e32 v232, v132
	v_exp_f32_e32 v235, v133
	v_exp_f32_e32 v236, v134
	v_exp_f32_e32 v239, v135
	v_exp_f32_e32 v212, v136
	v_exp_f32_e32 v215, v137
	v_exp_f32_e32 v216, v138
	v_exp_f32_e32 v233, v139
	v_exp_f32_e32 v234, v140
	v_exp_f32_e32 v237, v141
	v_exp_f32_e32 v238, v142
	v_exp_f32_e32 v240, v143
	s_waitcnt vmcnt(4) lgkmcnt(0)
	s_barrier
	s_add_i32 s10, s39, 0x8000
	s_and_b32 s48, s10, 0x1ffff
	s_add_i32 s10, s48, 0
	v_add_u32_e32 v96, s10, v202
	ds_read_b128 v[242:245], v96 offset:24576
	ds_read_b128 v[96:99], v96 offset:16384
	v_add_u32_e32 v241, s10, v201
	v_exp_f32_e32 v112, v112
	v_exp_f32_e32 v115, v115
	v_exp_f32_e32 v116, v116
	s_waitcnt lgkmcnt(0)
	v_mfma_f32_32x32x16_bf16 v[128:143], v[96:99], v[158:161], v[80:95]
	v_exp_f32_e32 v117, v117
	v_exp_f32_e32 v118, v118
	v_mfma_f32_32x32x16_bf16 v[96:111], v[242:245], v[158:161], v[80:95]
	ds_read_b128 v[242:245], v241 offset:24576
	ds_read_b128 v[246:249], v241 offset:16384
	v_add_u32_e32 v241, s10, v199
	ds_read_b128 v[68:71], v241 offset:24576
	ds_read_b128 v[72:75], v241 offset:16384
	v_add_u32_e32 v241, s10, v183
	s_waitcnt lgkmcnt(2)
	v_mfma_f32_32x32x16_bf16 v[128:143], v[246:249], v[154:157], v[128:143]
	v_mfma_f32_32x32x16_bf16 v[96:111], v[242:245], v[154:157], v[96:111]
	ds_read_b128 v[242:245], v241 offset:24576
	ds_read_b128 v[246:249], v241 offset:16384
	s_waitcnt lgkmcnt(2)
	v_mfma_f32_32x32x16_bf16 v[128:143], v[72:75], v[150:153], v[128:143]
	v_mfma_f32_32x32x16_bf16 v[96:111], v[68:71], v[150:153], v[96:111]
	v_exp_f32_e32 v241, v113
	v_add_f32_e32 v113, v213, v211
	v_add_f32_e32 v113, v214, v113
	v_add_f32_e32 v113, v217, v113
	v_add_f32_e32 v113, v232, v113
	v_add_f32_e32 v113, v235, v113
	v_add_f32_e32 v113, v236, v113
	v_add_f32_e32 v113, v239, v113
	v_add_f32_e32 v113, v212, v113
	v_add_f32_e32 v113, v215, v113
	v_add_f32_e32 v113, v216, v113
	v_add_f32_e32 v113, v233, v113
	v_add_f32_e32 v113, v234, v113
	v_add_f32_e32 v113, v237, v113
	s_waitcnt lgkmcnt(0)
	v_mfma_f32_32x32x16_bf16 v[96:111], v[242:245], v[146:149], v[96:111]
	v_exp_f32_e32 v242, v114
	v_add_f32_e32 v113, v238, v113
	v_add_f32_e32 v113, v240, v113
	v_add_f32_e32 v113, v112, v113
	v_add_f32_e32 v113, v241, v113
	v_add_f32_e32 v113, v242, v113
	v_exp_f32_e32 v243, v119
	v_add_f32_e32 v113, v115, v113
	v_exp_f32_e32 v119, v120
	v_add_f32_e32 v113, v116, v113
	v_exp_f32_e32 v120, v121
	v_add_f32_e32 v113, v117, v113
	v_exp_f32_e32 v121, v122
	v_add_f32_e32 v113, v118, v113
	v_exp_f32_e32 v122, v123
	v_add_f32_e32 v113, v243, v113
	v_exp_f32_e32 v123, v124
	v_add_f32_e32 v113, v119, v113
	v_exp_f32_e32 v124, v125
	v_add_f32_e32 v113, v120, v113
	v_mfma_f32_32x32x16_bf16 v[128:143], v[246:249], v[146:149], v[128:143]
	v_exp_f32_e32 v125, v126
	v_add_f32_e32 v113, v121, v113
	v_exp_f32_e32 v126, v127
	v_add_f32_e32 v113, v122, v113
	v_add_f32_e32 v113, v123, v113
	v_add_f32_e32 v113, v124, v113
	v_add_f32_e32 v113, v125, v113
	v_add_f32_e32 v113, v126, v113
	v_mov_b32_e32 v114, v113
	s_nop 1
	v_permlane32_swap_b32_e32 v113, v114
	v_cvt_pk_bf16_f32 v250, v211, v213
	v_cvt_pk_bf16_f32 v251, v214, v217
	v_cvt_pk_bf16_f32 v252, v232, v235
	v_cvt_pk_bf16_f32 v253, v236, v239
	v_cvt_pk_bf16_f32 v212, v212, v215
	v_cvt_pk_bf16_f32 v213, v216, v233
	v_cvt_pk_bf16_f32 v214, v234, v237
	v_cvt_pk_bf16_f32 v215, v238, v240
	v_cvt_pk_bf16_f32 v232, v112, v241
	v_cvt_pk_bf16_f32 v233, v242, v115
	v_cvt_pk_bf16_f32 v234, v116, v117
	v_cvt_pk_bf16_f32 v235, v118, v243
	v_cvt_pk_bf16_f32 v116, v119, v120
	v_cvt_pk_bf16_f32 v117, v121, v122
	v_cvt_pk_bf16_f32 v118, v123, v124
	v_cvt_pk_bf16_f32 v119, v125, v126
	v_add_u32_e32 v112, s39, v205
	ds_read_b64_tr_b16 v[120:121], v112 offset:0
	ds_read_b64_tr_b16 v[122:123], v112 offset:0x800
	ds_read_b64_tr_b16 v[124:125], v112 offset:0x1000
	ds_read_b64_tr_b16 v[126:127], v112 offset:0x1800
	ds_read_b64_tr_b16 v[236:237], v112 offset:0x2000
	ds_read_b64_tr_b16 v[238:239], v112 offset:0x2800
	ds_read_b64_tr_b16 v[240:241], v112 offset:0x3000
	ds_read_b64_tr_b16 v[242:243], v112 offset:0x3800
	s_cmp_gt_u32 s44, 60
	s_cselect_b64 s[52:53], -1, 0
	s_and_b64 vcc, exec, s[52:53]
	s_cbranch_vccnz .LBB0_204
	s_add_i32 s10, s56, 0x8000
	s_and_b32 s10, s10, 0x1ffff
	s_add_i32 s12, s21, s10
	s_add_u32 s98, s50, s68
	s_addc_u32 s99, s51, s69
	s_add_u32 s100, s50, 0x4040000
	s_addc_u32 s101, s51, 0
	s_add_i32 m0, s12, 0x4000
	s_add_u32 s10, s100, 0x80
	s_addc_u32 s11, s101, 0
	global_load_lds_dwordx4 v168, s[98:99]
	s_mov_b32 m0, s12
	s_nop 0
	global_load_lds_dwordx4 v188, s[100:101]
	s_add_i32 m0, s12, 0x4400
	s_nop 0
	global_load_lds_dwordx4 v170, s[98:99]
	s_add_i32 m0, s12, 0x400
	s_nop 0
	global_load_lds_dwordx4 v188, s[10:11]
; template <bool FIRST> __device__ __forceinline__ void partialSM(f32x16& p0, f32x16& p1, float& m_reg, f32x16& negm, float& alpha) {
;   float pmax = p0[0];
; #pragma unroll
;   for (int r = 1; r < 16; ++r) pmax = fmaxf(pmax, p0[r]);
; #pragma unroll
;   for (int r = 0; r < 16; ++r) pmax = fmaxf(pmax, p1[r]);
;   { auto rr = __builtin_amdgcn_permlane32_swap(__float_as_uint(pmax), __float_as_uint(pmax), false, false);
;     pmax = fmaxf(__uint_as_float(rr[0]), __uint_as_float(rr[1])); }
;   alpha = 1.f;
;   if (FIRST || __builtin_expect(__any(pmax > THR), 0)) { const float dl = FIRST ? pmax : fmaxf(pmax, 0.f); m_reg += dl; if (!FIRST) alpha = __builtin_amdgcn_exp2f(-dl);
; #pragma unroll
;     for (int r = 0; r < 16; ++r) { p0[r] -= dl; p1[r] -= dl; }
; #pragma unroll
;     for (int r = 0; r < 16; ++r) negm[r] = -m_reg; }
; #pragma unroll
;   for (int r = 0; r < 16; ++r) p0[r] = __builtin_amdgcn_exp2f(p0[r]);
; }
; __device__ __forceinline__ void finishSM(f32x16& p0, f32x16& p1, float alpha, float& l_reg, bf16x8& pa0, bf16x8& pa1, bf16x8& pa2, bf16x8& pa3) {
; #pragma unroll
;   for (int r = 0; r < 16; ++r) p1[r] = __builtin_amdgcn_exp2f(p1[r]);
;   float ps = 0;
; #pragma unroll
;   for (int r = 0; r < 16; ++r) ps += p0[r];
; #pragma unroll
;   for (int r = 0; r < 16; ++r) ps += p1[r];
;   { auto rr = __builtin_amdgcn_permlane32_swap(__float_as_uint(ps), __float_as_uint(ps), false, false);
;     ps = __uint_as_float(rr[0]) + __uint_as_float(rr[1]); }
;   l_reg = l_reg * alpha + ps;
;     ...
;   ATT_PKN(p0, 0, pa0); ATT_PKN(p0, 8, pa1); ATT_PKN(p1, 0, pa2); ATT_PKN(p1, 8, pa3);
;     ...
; }
; __device__ __forceinline__ void qkt(f32x16& p0, f32x16& p1, const bf16* Ks, const bf16x8* qr, int r32, int hi, int mp, const f32x16& negm) {
; #pragma unroll
;   for (int d0 = 0; d0 < 4; ++d0) { int cb = ((mp * 4 + d0) * 16 + hi * 8) * 2;
;     bf16x8 b0 = *reinterpret_cast<const bf16x8*>((const char*)Ks + KSWZ(r32, cb));
;     bf16x8 b1 = *reinterpret_cast<const bf16x8*>((const char*)Ks + KSWZ(32 + r32, cb));
;     if (d0 == 0) { p0 = __builtin_amdgcn_mfma_f32_32x32x16_bf16(b0, qr[0], negm, 0, 0, 0); p1 = __builtin_amdgcn_mfma_f32_32x32x16_bf16(b1, qr[0], negm, 0, 0, 0); }
;     else { p0 = __builtin_amdgcn_mfma_f32_32x32x16_bf16(b0, qr[d0], p0, 0, 0, 0); p1 = __builtin_amdgcn_mfma_f32_32x32x16_bf16(b1, qr[d0], p1, 0, 0, 0); } }
; }
.LBB0_204:
	s_waitcnt lgkmcnt(0)
	s_nop 0
	v_mfma_f32_32x32x16_bf16 v[0:15], v[250:253], v[120:123], v[0:15]
	ds_read_b64_tr_b16 v[120:121], v112 offset:0x200
	ds_read_b64_tr_b16 v[122:123], v112 offset:0xa00
	v_mfma_f32_32x32x16_bf16 v[0:15], v[212:215], v[124:127], v[0:15]
	ds_read_b64_tr_b16 v[124:125], v112 offset:0x1200
	ds_read_b64_tr_b16 v[126:127], v112 offset:0x1a00
	v_mfma_f32_32x32x16_bf16 v[0:15], v[232:235], v[236:239], v[0:15]
	ds_read_b64_tr_b16 v[236:237], v112 offset:0x2200
	ds_read_b64_tr_b16 v[238:239], v112 offset:0x2a00
	v_mfma_f32_32x32x16_bf16 v[0:15], v[116:119], v[240:243], v[0:15]
	ds_read_b64_tr_b16 v[240:241], v112 offset:0x3200
	ds_read_b64_tr_b16 v[242:243], v112 offset:0x3a00
	s_waitcnt lgkmcnt(0)
	v_mfma_f32_32x32x16_bf16 v[48:63], v[250:253], v[120:123], v[48:63]
	ds_read_b64_tr_b16 v[120:121], v112 offset:0x400
	ds_read_b64_tr_b16 v[122:123], v112 offset:0xc00
	v_mfma_f32_32x32x16_bf16 v[48:63], v[212:215], v[124:127], v[48:63]
	ds_read_b64_tr_b16 v[124:125], v112 offset:0x1400
	ds_read_b64_tr_b16 v[126:127], v112 offset:0x1c00
	v_mfma_f32_32x32x16_bf16 v[48:63], v[232:235], v[236:239], v[48:63]
	ds_read_b64_tr_b16 v[236:237], v112 offset:0x2400
	ds_read_b64_tr_b16 v[238:239], v112 offset:0x2c00
	v_mfma_f32_32x32x16_bf16 v[48:63], v[116:119], v[240:243], v[48:63]
	ds_read_b64_tr_b16 v[240:241], v112 offset:0x3400
	ds_read_b64_tr_b16 v[242:243], v112 offset:0x3c00
	s_waitcnt lgkmcnt(0)
	v_mfma_f32_32x32x16_bf16 v[32:47], v[250:253], v[120:123], v[32:47]
	ds_read_b64_tr_b16 v[120:121], v112 offset:0x600
	ds_read_b64_tr_b16 v[122:123], v112 offset:0xe00
	v_mfma_f32_32x32x16_bf16 v[32:47], v[212:215], v[124:127], v[32:47]
	ds_read_b64_tr_b16 v[124:125], v112 offset:0x1600
	ds_read_b64_tr_b16 v[126:127], v112 offset:0x1e00
	v_mfma_f32_32x32x16_bf16 v[32:47], v[232:235], v[236:239], v[32:47]
	ds_read_b64_tr_b16 v[236:237], v112 offset:0x2600
	ds_read_b64_tr_b16 v[238:239], v112 offset:0x2e00
	v_mfma_f32_32x32x16_bf16 v[32:47], v[116:119], v[240:243], v[32:47]
	ds_read_b64_tr_b16 v[240:241], v112 offset:0x3600
	ds_read_b64_tr_b16 v[242:243], v112 offset:0x3e00
	s_waitcnt lgkmcnt(0)
	v_mfma_f32_32x32x16_bf16 v[16:31], v[250:253], v[120:123], v[16:31]
	v_max_f32_e32 v112, v129, v129
	v_max_f32_e32 v115, v128, v128
	v_max_f32_e32 v112, v115, v112
	v_max3_f32 v112, v112, v130, v131
	v_max3_f32 v112, v112, v132, v133
	v_max3_f32 v112, v112, v134, v135
	v_max3_f32 v112, v112, v136, v137
	v_mfma_f32_32x32x16_bf16 v[16:31], v[212:215], v[124:127], v[16:31]
	v_max3_f32 v112, v112, v138, v139
	v_max3_f32 v112, v112, v140, v141
	v_max3_f32 v112, v112, v142, v143
	v_max3_f32 v112, v112, v96, v97
	v_max3_f32 v112, v112, v98, v99
	v_max3_f32 v112, v112, v100, v101
	v_max3_f32 v112, v112, v102, v103
	v_mfma_f32_32x32x16_bf16 v[16:31], v[232:235], v[236:239], v[16:31]
	v_max3_f32 v112, v112, v104, v105
	v_max3_f32 v112, v112, v106, v107
	v_max3_f32 v112, v112, v108, v109
	v_max3_f32 v112, v112, v110, v111
	v_mov_b32_e32 v115, v112
	s_nop 1
	v_permlane32_swap_b32_e32 v112, v115
	v_mfma_f32_32x32x16_bf16 v[16:31], v[116:119], v[240:243], v[16:31]
	v_max_f32_e32 v115, v112, v115
	v_cmp_lt_f32_e32 vcc, s19, v115
	v_mov_b32_e32 v112, 1.0
	s_cbranch_vccnz .LBB0_216
	s_branch .LBB0_209
